# full stack plus P3 epilogue row sums via permlane16/32 swap instead of ds_bpermute
# speedup vs baseline: 1.0022x; 1.0007x over previous
;     __device__ __forceinline__ void operator()(const f32x4 (&acc)[2][2][4][2], const Unit& u, int wr, int wc, int fr, int fq) const {
;         const int row0 = u.pm * BM + wr * 64 + fr, col0 = u.pn * BM + wc * 32 + 4 * fq;
;         float r2[8];
;         int rown = row0; asm volatile("" : "+v"(rown));
; #pragma unroll
;         for (int g = 0; g < 8; ++g) { if constexpr (HAS_RS2) r2[g] = __hip_atomic_load(rs2 + row0 + (g >> 2) * HALF + (g & 3) * 16, __ATOMIC_RELAXED, __HIP_MEMORY_SCOPE_AGENT); else if constexpr (HAS_NRM) r2[g] = ssq[NRM_OFF + rown + (g >> 2) * HALF + (g & 3) * 16]; else r2[g] = 0.f; }
;         u32x2 raw[8][2][2];
;         if constexpr (BASEB) {
; #pragma unroll
;             for (int g = 0; g < 4; ++g)
; #pragma unroll
;                 for (int bj = 0; bj < 2; ++bj)
; #pragma unroll
;                     for (int n = 0; n < 2; ++n) raw[g][bj][n] = *(const u32x2*)((const bf16_t*)base + (size_t)(row0 + (g >> 2) * HALF + (g & 3) * 16) * 2048 + col0 + bj * HALF + n * 16);
;         }
;         f32x4 nx[2][2], ny[2][2]; if constexpr (!BASEB) { ldbase(nx, (size_t)row0 * 2048 + col0); ldbase(ny, (size_t)(row0 + 16) * 2048 + col0); }
; #pragma unroll
;         for (int g = 0; g < 8; ++g) { if constexpr (HAS_RS2) r2[g] = __builtin_amdgcn_rcpf(r2[g] * (1.0f / 2048.0f) + 1e-5f); else if constexpr (HAS_NRM) r2[g] = __builtin_amdgcn_sqrtf(r2[g] * (1.0f / 2048.0f) + 1e-5f);     else r2[g] = 1.f; }
; #pragma unroll
;         for (int g = 0; g < 8; ++g) {
;             const int ai = g >> 2, m = g & 3;
;             const int row = row0 + ai * HALF + m * 16; const size_t off = (size_t)row * 2048 + col0; float s = 0.f;
;             f32x4 bs[2][2];
;             if constexpr (BASEB) {
;                 if (g < 4) {
; #pragma unroll
;                     for (int bj = 0; bj < 2; ++bj)
; #pragma unroll
;                         for (int n = 0; n < 2; ++n) raw[g + 4][bj][n] = *(const u32x2*)((const bf16_t*)base + (size_t)(row0 + ((g + 4) >> 2) * HALF + ((g + 4) & 3) * 16) * 2048 + col0 + bj * HALF + n * 16);
;                 }
; #pragma unroll
;                 for (int bj = 0; bj < 2; ++bj)
; #pragma unroll
;                     for (int n = 0; n < 2; ++n) bs[bj][n] = bf4_to_f32(raw[g][bj][n]);
;             } else {
; #pragma unroll
;             for (int bj = 0; bj < 2; ++bj)
; #pragma unroll
.LBB0_654:
	v_lshl_add_u32 v182, s24, 8, v1
	v_lshl_or_b32 v140, s22, 8, v196
	v_mov_b32_e32 v142, v182
	v_ashrrev_i32_e32 v141, 31, v140
	v_lshlrev_b64 v[156:157], 1, v[140:141]
	v_ashrrev_i32_e32 v183, 31, v182
	v_ashrrev_i32_e32 v143, 31, v142
	v_lshl_add_u64 v[148:149], s[90:91], 0, v[156:157]
	v_lshlrev_b64 v[210:211], 12, v[182:183]
	v_lshl_add_u64 v[142:143], v[142:143], 2, s[6:7]
	v_lshl_add_u64 v[144:145], v[148:149], 0, v[210:211]
	v_add_co_u32_e32 v216, vcc, 0x20000, v142
	global_load_dwordx2 v[212:213], v[144:145], off
	global_load_dwordx2 v[214:215], v[144:145], off offset:32
	global_load_dwordx2 v[218:219], v[144:145], off offset:256
	v_addc_co_u32_e32 v217, vcc, 0, v143, vcc
	global_load_dwordx2 v[220:221], v[144:145], off offset:288
	global_load_dword v209, v[216:217], off
	v_or_b32_e32 v172, 16, v182
	v_or_b32_e32 v160, 32, v182
	v_or_b32_e32 v146, 48, v182
	v_add_u32_e32 v142, 0x80, v182
	v_ashrrev_i32_e32 v173, 31, v172
	v_ashrrev_i32_e32 v161, 31, v160
	v_ashrrev_i32_e32 v147, 31, v146
	v_ashrrev_i32_e32 v143, 31, v142
	v_lshlrev_b64 v[184:185], 12, v[172:173]
	v_lshlrev_b64 v[170:171], 12, v[160:161]
	v_lshlrev_b64 v[158:159], 12, v[146:147]
	v_lshlrev_b64 v[144:145], 12, v[142:143]
	v_lshl_add_u64 v[150:151], v[148:149], 0, v[184:185]
	v_lshl_add_u64 v[152:153], v[148:149], 0, v[170:171]
	v_lshl_add_u64 v[148:149], v[148:149], 0, v[158:159]
	v_lshl_add_u64 v[154:155], s[90:91], 0, v[144:145]
	global_load_dwordx2 v[192:193], v[150:151], off
	global_load_dwordx2 v[190:191], v[150:151], off offset:32
	global_load_dwordx2 v[188:189], v[150:151], off offset:256
	global_load_dwordx2 v[186:187], v[150:151], off offset:288
	global_load_dwordx2 v[180:181], v[152:153], off
	global_load_dwordx2 v[178:179], v[152:153], off offset:32
	global_load_dwordx2 v[176:177], v[152:153], off offset:256
	global_load_dwordx2 v[174:175], v[152:153], off offset:288
	global_load_dwordx2 v[168:169], v[148:149], off
	global_load_dwordx2 v[166:167], v[148:149], off offset:32
	global_load_dwordx2 v[164:165], v[148:149], off offset:256
	global_load_dwordx2 v[162:163], v[148:149], off offset:288
	v_lshl_add_u64 v[148:149], v[154:155], 0, v[156:157]
	global_load_dwordx2 v[154:155], v[148:149], off
	global_load_dwordx2 v[152:153], v[148:149], off offset:32
	global_load_dwordx2 v[150:151], v[148:149], off offset:256
	s_nop 0
	global_load_dwordx2 v[148:149], v[148:149], off offset:288
	s_nop 0
	global_load_dword v208, v[216:217], off offset:64
	global_load_dword v207, v[216:217], off offset:128
	global_load_dword v206, v[216:217], off offset:192
	global_load_dword v205, v[216:217], off offset:512
	global_load_dword v204, v[216:217], off offset:576
	global_load_dword v203, v[216:217], off offset:640
	global_load_dword v202, v[216:217], off offset:704
	v_lshl_add_u64 v[210:211], s[70:71], 0, v[210:211]
	v_lshl_add_u64 v[210:211], v[210:211], 0, v[156:157]
	s_waitcnt vmcnt(0)
	v_lshlrev_b32_e32 v216, 16, v212
	v_and_b32_e32 v217, 0xffff0000, v212
	v_lshlrev_b32_e32 v212, 16, v213
	v_and_b32_e32 v213, 0xffff0000, v213
	v_lshlrev_b32_e32 v222, 16, v214
	v_fmamk_f32 v209, v209, 0x3a000000, v200
	v_sqrt_f32_e32 v228, v209
	v_and_b32_e32 v223, 0xffff0000, v214
	v_lshlrev_b32_e32 v214, 16, v215
	v_and_b32_e32 v215, 0xffff0000, v215
	v_pk_fma_f32 v[128:129], v[228:229], v[212:213], v[128:129] op_sel_hi:[0,1,1]
	v_pk_fma_f32 v[126:127], v[228:229], v[216:217], v[126:127] op_sel_hi:[0,1,1]
	v_pk_fma_f32 v[124:125], v[228:229], v[214:215], v[124:125] op_sel_hi:[0,1,1]
	v_pk_fma_f32 v[122:123], v[228:229], v[222:223], v[122:123] op_sel_hi:[0,1,1]
	v_mul_f32_e32 v214, v129, v129
	v_mul_f32_e32 v209, v127, v127
	v_cvt_pk_bf16_f32 v212, v126, v127
	v_cvt_pk_bf16_f32 v213, v128, v129
	v_mul_f32_e32 v127, v123, v123
	v_fmac_f32_e32 v214, v128, v128
	v_mul_f32_e32 v128, v125, v125
	v_lshlrev_b32_e32 v224, 16, v218
	v_and_b32_e32 v225, 0xffff0000, v218
	v_lshlrev_b32_e32 v218, 16, v219
	v_and_b32_e32 v219, 0xffff0000, v219
	v_fmac_f32_e32 v209, v126, v126
	v_fmac_f32_e32 v127, v122, v122
	v_fmac_f32_e32 v128, v124, v124
	v_lshlrev_b32_e32 v226, 16, v220
	v_and_b32_e32 v227, 0xffff0000, v220
	v_lshlrev_b32_e32 v220, 16, v221
	v_and_b32_e32 v221, 0xffff0000, v221
	v_add_f32_e32 v126, v209, v214
	v_add_f32_e32 v127, v127, v128
	v_pk_fma_f32 v[120:121], v[228:229], v[218:219], v[120:121] op_sel_hi:[0,1,1]
	v_pk_fma_f32 v[118:119], v[228:229], v[224:225], v[118:119] op_sel_hi:[0,1,1]
	global_store_dwordx2 v[210:211], v[212:213], off
	v_add_f32_e32 v126, v126, v127
	v_cvt_pk_bf16_f32 v122, v122, v123
	v_mul_f32_e32 v123, v119, v119
	v_mul_f32_e32 v127, v121, v121
	v_pk_fma_f32 v[116:117], v[228:229], v[220:221], v[116:117] op_sel_hi:[0,1,1]
	v_pk_fma_f32 v[128:129], v[228:229], v[226:227], v[114:115] op_sel_hi:[0,1,1]
	v_fmac_f32_e32 v123, v118, v118
	v_fmac_f32_e32 v127, v120, v120
	v_mul_f32_e32 v114, v129, v129
	v_mul_f32_e32 v115, v117, v117
	v_add_f32_e32 v123, v123, v127
	v_fmac_f32_e32 v114, v128, v128
	v_fmac_f32_e32 v115, v116, v116
	v_add_f32_e32 v123, v126, v123
	v_add_f32_e32 v114, v114, v115
	v_add_f32_e32 v114, v123, v114
	v_and_b32_e32 v123, 64, v201
	v_xor_b32_e32 v115, 16, v201
	v_add_u32_e32 v127, 64, v123
	v_cmp_lt_i32_e32 vcc, v115, v127
	v_cvt_pk_bf16_f32 v123, v124, v125
	global_store_dwordx2 v[210:211], v[122:123], off offset:32
	v_cvt_pk_bf16_f32 v118, v118, v119
	v_cvt_pk_bf16_f32 v119, v120, v121
	global_store_dwordx2 v[210:211], v[118:119], off offset:256
	v_cndmask_b32_e32 v115, v201, v115, vcc
	v_lshlrev_b32_e32 v126, 2, v115
	v_mov_b32_e32 v115, v114
	s_nop 1
	v_permlane16_swap_b32_e32 v115, v114
	v_cvt_pk_bf16_f32 v118, v128, v129
	v_cvt_pk_bf16_f32 v119, v116, v117
	global_store_dwordx2 v[210:211], v[118:119], off offset:288
	s_waitcnt lgkmcnt(0)
	v_add_f32_e32 v114, v114, v115
	v_xor_b32_e32 v115, 32, v201
	v_cmp_lt_i32_e32 vcc, v115, v127
	s_nop 1
	v_cndmask_b32_e32 v115, v201, v115, vcc
	v_lshlrev_b32_e32 v127, 2, v115
	v_mov_b32_e32 v115, v114
	s_nop 1
	v_permlane32_swap_b32_e32 v115, v114
	s_and_saveexec_b64 s[22:23], s[4:5]
	s_cbranch_execz .LBB0_656
	v_lshl_add_u64 v[116:117], v[182:183], 2, s[6:7]
	s_waitcnt lgkmcnt(0)
	v_add_f32_e32 v114, v114, v115
	global_atomic_add_f32 v[116:117], v114, off
; __device__ __forceinline__ unsigned cvt_pk_bf16(float lo, float hi) { unsigned r; asm volatile("v_cvt_pk_bf16_f32 %0, %1, %2" : "=v"(r) : "v"(lo), "v"(hi)); return r; }
; __device__ __forceinline__ f32x4 bf4_to_f32(u32x2 w) { f32x4 r; r[0] = __uint_as_float(w.x << 16); r[1] = __uint_as_float(w.x & 0xffff0000u); r[2] = __uint_as_float(w.y << 16); r[3] = __uint_as_float(w.y & 0xffff0000u); return r; }
;     __device__ __forceinline__ void operator()(const f32x4 (&acc)[2][2][4][2], const Unit& u, int wr, int wc, int fr, int fq) const {
;     ...
;         for (int g = 0; g < 8; ++g) {
;             const int ai = g >> 2, m = g & 3;
;             const int row = row0 + ai * HALF + m * 16; const size_t off = (size_t)row * 2048 + col0; float s = 0.f;
;             f32x4 bs[2][2];
;             if constexpr (BASEB) {
;                 if (g < 4) {
; #pragma unroll
;                     for (int bj = 0; bj < 2; ++bj)
; #pragma unroll
;                         for (int n = 0; n < 2; ++n) raw[g + 4][bj][n] = *(const u32x2*)((const bf16_t*)base + (size_t)(row0 + ((g + 4) >> 2) * HALF + ((g + 4) & 3) * 16) * 2048 + col0 + bj * HALF + n * 16);
;                 }
; #pragma unroll
;                 for (int bj = 0; bj < 2; ++bj)
; #pragma unroll
;                     for (int n = 0; n < 2; ++n) bs[bj][n] = bf4_to_f32(raw[g][bj][n]);
;             } else {
; #pragma unroll
;             for (int bj = 0; bj < 2; ++bj)
; #pragma unroll
;                 for (int n = 0; n < 2; ++n) { bs[bj][n] = nx[bj][n]; nx[bj][n] = ny[bj][n]; }
;             if (g < 6) ldbase(ny, (size_t)(row0 + ((g + 2) >> 2) * HALF + ((g + 2) & 3) * 16) * 2048 + col0);
;             }
; #pragma unroll
;             for (int bj = 0; bj < 2; ++bj)
; #pragma unroll
;                 for (int n = 0; n < 2; ++n) {
;                     const f32x4 o = HAS_NRM ? (bs[bj][n] * r2[g] + acc[ai][bj][m][n]) : (bs[bj][n] + acc[ai][bj][m][n] * r2[g]);
;                     if (HAS_OUT) *(f32x4*)(out + off + bj * HALF + n * 16) = o;
;                     s += (o[0] * o[0] + o[1] * o[1]) + (o[2] * o[2] + o[3] * o[3]);
;                     if (HAS_OUTB) { u32x2 w; w.x = cvt_pk_bf16(o[0], o[1]); w.y = cvt_pk_bf16(o[2], o[3]); *(u32x2*)(outb + off + bj * HALF + n * 16) = w; }
;                 }
;             s += __shfl_xor(s, 16); s += __shfl_xor(s, 32);
;             if (fq == 0) unsafeAtomicAdd(ssq + row, s);
.LBB0_656:
	s_or_b64 exec, exec, s[22:23]
	v_or_b32_e32 v114, 16, v142
	s_waitcnt lgkmcnt(0)
	v_ashrrev_i32_e32 v115, 31, v114
	v_lshlrev_b64 v[116:117], 12, v[114:115]
	v_lshl_add_u64 v[118:119], s[90:91], 0, v[116:117]
	v_lshl_add_u64 v[118:119], v[118:119], 0, v[156:157]
	global_load_dwordx2 v[124:125], v[118:119], off
	global_load_dwordx2 v[122:123], v[118:119], off offset:32
	global_load_dwordx2 v[120:121], v[118:119], off offset:256
	s_nop 0
	global_load_dwordx2 v[118:119], v[118:119], off offset:288
	v_fmamk_f32 v128, v208, 0x3a000000, v200
	v_sqrt_f32_e32 v128, v128
	v_lshlrev_b32_e32 v182, 16, v192
	v_and_b32_e32 v183, 0xffff0000, v192
	v_lshlrev_b32_e32 v192, 16, v193
	v_and_b32_e32 v193, 0xffff0000, v193
	v_pk_fma_f32 v[112:113], v[128:129], v[192:193], v[112:113] op_sel_hi:[0,1,1]
	v_pk_fma_f32 v[110:111], v[128:129], v[182:183], v[110:111] op_sel_hi:[0,1,1]
	v_mul_f32_e32 v129, v111, v111
	v_mul_f32_e32 v182, v113, v113
	v_fmac_f32_e32 v129, v110, v110
	v_fmac_f32_e32 v182, v112, v112
	v_lshlrev_b32_e32 v208, 16, v190
	v_and_b32_e32 v209, 0xffff0000, v190
	v_lshlrev_b32_e32 v190, 16, v191
	v_and_b32_e32 v191, 0xffff0000, v191
	v_add_f32_e32 v129, v129, v182
	v_cvt_pk_bf16_f32 v110, v110, v111
	v_cvt_pk_bf16_f32 v111, v112, v113
	v_lshl_add_u64 v[112:113], s[70:71], 0, v[184:185]
	v_lshl_add_u64 v[112:113], v[112:113], 0, v[156:157]
	v_pk_fma_f32 v[108:109], v[128:129], v[190:191], v[108:109] op_sel_hi:[0,1,1]
	v_pk_fma_f32 v[106:107], v[128:129], v[208:209], v[106:107] op_sel_hi:[0,1,1]
	v_lshlrev_b32_e32 v210, 16, v188
	v_and_b32_e32 v211, 0xffff0000, v188
	v_lshlrev_b32_e32 v188, 16, v189
	v_and_b32_e32 v189, 0xffff0000, v189
	global_store_dwordx2 v[112:113], v[110:111], off
	v_mul_f32_e32 v110, v107, v107
	v_mul_f32_e32 v111, v109, v109
	v_fmac_f32_e32 v110, v106, v106
	v_fmac_f32_e32 v111, v108, v108
	v_pk_fma_f32 v[104:105], v[128:129], v[188:189], v[104:105] op_sel_hi:[0,1,1]
	v_pk_fma_f32 v[102:103], v[128:129], v[210:211], v[102:103] op_sel_hi:[0,1,1]
	v_add_f32_e32 v110, v110, v111
	v_cvt_pk_bf16_f32 v106, v106, v107
	v_mul_f32_e32 v107, v103, v103
	v_mul_f32_e32 v111, v105, v105
	v_fmac_f32_e32 v107, v102, v102
	v_fmac_f32_e32 v111, v104, v104
	v_lshlrev_b32_e32 v212, 16, v186
	v_and_b32_e32 v213, 0xffff0000, v186
	v_lshlrev_b32_e32 v186, 16, v187
	v_and_b32_e32 v187, 0xffff0000, v187
	v_add_f32_e32 v110, v129, v110
	v_add_f32_e32 v107, v107, v111
	v_add_f32_e32 v107, v110, v107
	v_pk_fma_f32 v[100:101], v[128:129], v[186:187], v[100:101] op_sel_hi:[0,1,1]
	v_pk_fma_f32 v[110:111], v[128:129], v[212:213], v[98:99] op_sel_hi:[0,1,1]
	v_mul_f32_e32 v98, v111, v111
	v_mul_f32_e32 v99, v101, v101
	v_fmac_f32_e32 v98, v110, v110
	v_fmac_f32_e32 v99, v100, v100
	v_add_f32_e32 v98, v98, v99
	v_add_f32_e32 v98, v107, v98
	v_mov_b32_e32 v99, v98
	s_nop 1
	v_permlane16_swap_b32_e32 v99, v98
	v_cvt_pk_bf16_f32 v107, v108, v109
	global_store_dwordx2 v[112:113], v[106:107], off offset:32
	v_cvt_pk_bf16_f32 v102, v102, v103
	v_cvt_pk_bf16_f32 v103, v104, v105
	s_waitcnt lgkmcnt(0)
	v_add_f32_e32 v98, v98, v99
	v_mov_b32_e32 v99, v98
	s_nop 1
	v_permlane32_swap_b32_e32 v99, v98
	global_store_dwordx2 v[112:113], v[102:103], off offset:256
	v_cvt_pk_bf16_f32 v102, v110, v111
	v_cvt_pk_bf16_f32 v103, v100, v101
	global_store_dwordx2 v[112:113], v[102:103], off offset:288
	s_and_saveexec_b64 s[22:23], s[4:5]
	s_cbranch_execz .LBB0_658
	v_lshl_add_u64 v[100:101], v[172:173], 2, s[6:7]
	s_waitcnt lgkmcnt(0)
	v_add_f32_e32 v98, v98, v99
	global_atomic_add_f32 v[100:101], v98, off
.LBB0_658:
	s_or_b64 exec, exec, s[22:23]
	v_or_b32_e32 v98, 32, v142
	s_waitcnt lgkmcnt(0)
	v_ashrrev_i32_e32 v99, 31, v98
	v_lshlrev_b64 v[100:101], 12, v[98:99]
	v_lshl_add_u64 v[102:103], s[90:91], 0, v[100:101]
	v_lshl_add_u64 v[102:103], v[102:103], 0, v[156:157]
	global_load_dwordx2 v[108:109], v[102:103], off
	global_load_dwordx2 v[106:107], v[102:103], off offset:32
	global_load_dwordx2 v[104:105], v[102:103], off offset:256
	s_nop 0
	global_load_dwordx2 v[102:103], v[102:103], off offset:288
	v_fmamk_f32 v110, v207, 0x3a000000, v200
	v_sqrt_f32_e32 v110, v110
	v_lshlrev_b32_e32 v112, 16, v180
	v_and_b32_e32 v113, 0xffff0000, v180
	v_lshlrev_b32_e32 v128, 16, v181
	v_and_b32_e32 v129, 0xffff0000, v181
	v_pk_fma_f32 v[96:97], v[110:111], v[128:129], v[96:97] op_sel_hi:[0,1,1]
	v_pk_fma_f32 v[94:95], v[110:111], v[112:113], v[94:95] op_sel_hi:[0,1,1]
	v_mul_f32_e32 v111, v95, v95
	v_mul_f32_e32 v112, v97, v97
	v_fmac_f32_e32 v111, v94, v94
	v_fmac_f32_e32 v112, v96, v96
	v_lshlrev_b32_e32 v172, 16, v178
	v_and_b32_e32 v173, 0xffff0000, v178
	v_lshlrev_b32_e32 v178, 16, v179
	v_and_b32_e32 v179, 0xffff0000, v179
	v_add_f32_e32 v111, v111, v112
	v_cvt_pk_bf16_f32 v94, v94, v95
	v_cvt_pk_bf16_f32 v95, v96, v97
	v_lshl_add_u64 v[96:97], s[70:71], 0, v[170:171]
	v_lshl_add_u64 v[96:97], v[96:97], 0, v[156:157]
	v_pk_fma_f32 v[92:93], v[110:111], v[178:179], v[92:93] op_sel_hi:[0,1,1]
	v_pk_fma_f32 v[90:91], v[110:111], v[172:173], v[90:91] op_sel_hi:[0,1,1]
	v_lshlrev_b32_e32 v180, 16, v176
	v_and_b32_e32 v181, 0xffff0000, v176
	v_lshlrev_b32_e32 v176, 16, v177
	v_and_b32_e32 v177, 0xffff0000, v177
	global_store_dwordx2 v[96:97], v[94:95], off
	v_mul_f32_e32 v94, v91, v91
	v_mul_f32_e32 v95, v93, v93
	v_fmac_f32_e32 v94, v90, v90
	v_fmac_f32_e32 v95, v92, v92
	v_pk_fma_f32 v[88:89], v[110:111], v[176:177], v[88:89] op_sel_hi:[0,1,1]
	v_pk_fma_f32 v[86:87], v[110:111], v[180:181], v[86:87] op_sel_hi:[0,1,1]
	v_add_f32_e32 v94, v94, v95
	v_cvt_pk_bf16_f32 v90, v90, v91
	v_mul_f32_e32 v91, v87, v87
	v_mul_f32_e32 v95, v89, v89
	v_fmac_f32_e32 v91, v86, v86
	v_fmac_f32_e32 v95, v88, v88
	v_lshlrev_b32_e32 v182, 16, v174
	v_and_b32_e32 v183, 0xffff0000, v174
	v_lshlrev_b32_e32 v174, 16, v175
	v_and_b32_e32 v175, 0xffff0000, v175
	v_add_f32_e32 v94, v111, v94
	v_add_f32_e32 v91, v91, v95
	v_add_f32_e32 v91, v94, v91
	v_pk_fma_f32 v[84:85], v[110:111], v[174:175], v[84:85] op_sel_hi:[0,1,1]
	v_pk_fma_f32 v[94:95], v[110:111], v[182:183], v[82:83] op_sel_hi:[0,1,1]
	v_mul_f32_e32 v82, v95, v95
	v_mul_f32_e32 v83, v85, v85
	v_fmac_f32_e32 v82, v94, v94
	v_fmac_f32_e32 v83, v84, v84
	v_add_f32_e32 v82, v82, v83
	v_add_f32_e32 v82, v91, v82
	v_mov_b32_e32 v83, v82
	s_nop 1
	v_permlane16_swap_b32_e32 v83, v82
	v_cvt_pk_bf16_f32 v91, v92, v93
	global_store_dwordx2 v[96:97], v[90:91], off offset:32
	v_cvt_pk_bf16_f32 v86, v86, v87
	v_cvt_pk_bf16_f32 v87, v88, v89
	s_waitcnt lgkmcnt(0)
	v_add_f32_e32 v82, v82, v83
	v_mov_b32_e32 v83, v82
	s_nop 1
	v_permlane32_swap_b32_e32 v83, v82
	global_store_dwordx2 v[96:97], v[86:87], off offset:256
	v_cvt_pk_bf16_f32 v86, v94, v95
	v_cvt_pk_bf16_f32 v87, v84, v85
	global_store_dwordx2 v[96:97], v[86:87], off offset:288
	s_and_saveexec_b64 s[22:23], s[4:5]
	s_cbranch_execz .LBB0_660
	v_lshl_add_u64 v[84:85], v[160:161], 2, s[6:7]
	s_waitcnt lgkmcnt(0)
	v_add_f32_e32 v82, v82, v83
	global_atomic_add_f32 v[84:85], v82, off
; __device__ __forceinline__ unsigned cvt_pk_bf16(float lo, float hi) { unsigned r; asm volatile("v_cvt_pk_bf16_f32 %0, %1, %2" : "=v"(r) : "v"(lo), "v"(hi)); return r; }
; __device__ __forceinline__ f32x4 bf4_to_f32(u32x2 w) { f32x4 r; r[0] = __uint_as_float(w.x << 16); r[1] = __uint_as_float(w.x & 0xffff0000u); r[2] = __uint_as_float(w.y << 16); r[3] = __uint_as_float(w.y & 0xffff0000u); return r; }
;     __device__ __forceinline__ void operator()(const f32x4 (&acc)[2][2][4][2], const Unit& u, int wr, int wc, int fr, int fq) const {
;     ...
;         for (int g = 0; g < 8; ++g) {
;             const int ai = g >> 2, m = g & 3;
;             const int row = row0 + ai * HALF + m * 16; const size_t off = (size_t)row * 2048 + col0; float s = 0.f;
;             f32x4 bs[2][2];
;             if constexpr (BASEB) {
;                 if (g < 4) {
; #pragma unroll
;                     for (int bj = 0; bj < 2; ++bj)
; #pragma unroll
;                         for (int n = 0; n < 2; ++n) raw[g + 4][bj][n] = *(const u32x2*)((const bf16_t*)base + (size_t)(row0 + ((g + 4) >> 2) * HALF + ((g + 4) & 3) * 16) * 2048 + col0 + bj * HALF + n * 16);
;                 }
; #pragma unroll
;                 for (int bj = 0; bj < 2; ++bj)
; #pragma unroll
;                     for (int n = 0; n < 2; ++n) bs[bj][n] = bf4_to_f32(raw[g][bj][n]);
;             } else {
; #pragma unroll
;             for (int bj = 0; bj < 2; ++bj)
; #pragma unroll
;                 for (int n = 0; n < 2; ++n) { bs[bj][n] = nx[bj][n]; nx[bj][n] = ny[bj][n]; }
;             if (g < 6) ldbase(ny, (size_t)(row0 + ((g + 2) >> 2) * HALF + ((g + 2) & 3) * 16) * 2048 + col0);
;             }
; #pragma unroll
;             for (int bj = 0; bj < 2; ++bj)
; #pragma unroll
;                 for (int n = 0; n < 2; ++n) {
;                     const f32x4 o = HAS_NRM ? (bs[bj][n] * r2[g] + acc[ai][bj][m][n]) : (bs[bj][n] + acc[ai][bj][m][n] * r2[g]);
;                     if (HAS_OUT) *(f32x4*)(out + off + bj * HALF + n * 16) = o;
;                     s += (o[0] * o[0] + o[1] * o[1]) + (o[2] * o[2] + o[3] * o[3]);
;                     if (HAS_OUTB) { u32x2 w; w.x = cvt_pk_bf16(o[0], o[1]); w.y = cvt_pk_bf16(o[2], o[3]); *(u32x2*)(outb + off + bj * HALF + n * 16) = w; }
;                 }
;             s += __shfl_xor(s, 16); s += __shfl_xor(s, 32);
;             if (fq == 0) unsafeAtomicAdd(ssq + row, s);
.LBB0_660:
	s_or_b64 exec, exec, s[22:23]
	v_or_b32_e32 v82, 48, v142
	s_waitcnt lgkmcnt(0)
	v_ashrrev_i32_e32 v83, 31, v82
	v_lshlrev_b64 v[84:85], 12, v[82:83]
	v_lshl_add_u64 v[86:87], s[90:91], 0, v[84:85]
	v_lshl_add_u64 v[86:87], v[86:87], 0, v[156:157]
	global_load_dwordx2 v[92:93], v[86:87], off
	global_load_dwordx2 v[90:91], v[86:87], off offset:32
	global_load_dwordx2 v[88:89], v[86:87], off offset:256
	s_nop 0
	global_load_dwordx2 v[86:87], v[86:87], off offset:288
	v_fmamk_f32 v94, v206, 0x3a000000, v200
	v_sqrt_f32_e32 v94, v94
	v_lshlrev_b32_e32 v96, 16, v168
	v_and_b32_e32 v97, 0xffff0000, v168
	v_lshlrev_b32_e32 v110, 16, v169
	v_and_b32_e32 v111, 0xffff0000, v169
	v_pk_fma_f32 v[80:81], v[94:95], v[110:111], v[80:81] op_sel_hi:[0,1,1]
	v_pk_fma_f32 v[78:79], v[94:95], v[96:97], v[78:79] op_sel_hi:[0,1,1]
	v_mul_f32_e32 v95, v79, v79
	v_mul_f32_e32 v96, v81, v81
	v_fmac_f32_e32 v95, v78, v78
	v_fmac_f32_e32 v96, v80, v80
	v_lshlrev_b32_e32 v112, 16, v166
	v_and_b32_e32 v113, 0xffff0000, v166
	v_lshlrev_b32_e32 v128, 16, v167
	v_and_b32_e32 v129, 0xffff0000, v167
	v_add_f32_e32 v95, v95, v96
	v_cvt_pk_bf16_f32 v78, v78, v79
	v_cvt_pk_bf16_f32 v79, v80, v81
	v_lshl_add_u64 v[80:81], s[70:71], 0, v[158:159]
	v_lshl_add_u64 v[80:81], v[80:81], 0, v[156:157]
	v_pk_fma_f32 v[76:77], v[94:95], v[128:129], v[76:77] op_sel_hi:[0,1,1]
	v_pk_fma_f32 v[74:75], v[94:95], v[112:113], v[74:75] op_sel_hi:[0,1,1]
	v_lshlrev_b32_e32 v160, 16, v164
	v_and_b32_e32 v161, 0xffff0000, v164
	v_lshlrev_b32_e32 v164, 16, v165
	v_and_b32_e32 v165, 0xffff0000, v165
	global_store_dwordx2 v[80:81], v[78:79], off
	v_mul_f32_e32 v78, v75, v75
	v_mul_f32_e32 v79, v77, v77
	v_fmac_f32_e32 v78, v74, v74
	v_fmac_f32_e32 v79, v76, v76
	v_pk_fma_f32 v[72:73], v[94:95], v[164:165], v[72:73] op_sel_hi:[0,1,1]
	v_pk_fma_f32 v[70:71], v[94:95], v[160:161], v[70:71] op_sel_hi:[0,1,1]
	v_add_f32_e32 v78, v78, v79
	v_cvt_pk_bf16_f32 v74, v74, v75
	v_mul_f32_e32 v75, v71, v71
	v_mul_f32_e32 v79, v73, v73
	v_fmac_f32_e32 v75, v70, v70
	v_fmac_f32_e32 v79, v72, v72
	v_lshlrev_b32_e32 v166, 16, v162
	v_and_b32_e32 v167, 0xffff0000, v162
	v_lshlrev_b32_e32 v162, 16, v163
	v_and_b32_e32 v163, 0xffff0000, v163
	v_add_f32_e32 v78, v95, v78
	v_add_f32_e32 v75, v75, v79
	v_add_f32_e32 v75, v78, v75
	v_pk_fma_f32 v[68:69], v[94:95], v[162:163], v[68:69] op_sel_hi:[0,1,1]
	v_pk_fma_f32 v[78:79], v[94:95], v[166:167], v[66:67] op_sel_hi:[0,1,1]
	v_mul_f32_e32 v66, v79, v79
	v_mul_f32_e32 v67, v69, v69
	v_fmac_f32_e32 v66, v78, v78
	v_fmac_f32_e32 v67, v68, v68
	v_add_f32_e32 v66, v66, v67
	v_add_f32_e32 v66, v75, v66
	v_mov_b32_e32 v67, v66
	s_nop 1
	v_permlane16_swap_b32_e32 v67, v66
	v_cvt_pk_bf16_f32 v75, v76, v77
	global_store_dwordx2 v[80:81], v[74:75], off offset:32
	v_cvt_pk_bf16_f32 v70, v70, v71
	v_cvt_pk_bf16_f32 v71, v72, v73
	s_waitcnt lgkmcnt(0)
	v_add_f32_e32 v66, v66, v67
	v_mov_b32_e32 v67, v66
	s_nop 1
	v_permlane32_swap_b32_e32 v67, v66
	global_store_dwordx2 v[80:81], v[70:71], off offset:256
	v_cvt_pk_bf16_f32 v70, v78, v79
	v_cvt_pk_bf16_f32 v71, v68, v69
	global_store_dwordx2 v[80:81], v[70:71], off offset:288
	s_and_saveexec_b64 s[22:23], s[4:5]
	s_cbranch_execz .LBB0_662
	v_lshl_add_u64 v[68:69], v[146:147], 2, s[6:7]
	s_waitcnt lgkmcnt(0)
	v_add_f32_e32 v66, v66, v67
	global_atomic_add_f32 v[68:69], v66, off
.LBB0_662:
	s_or_b64 exec, exec, s[22:23]
	v_fmamk_f32 v66, v205, 0x3a000000, v200
	v_sqrt_f32_e32 v66, v66
	v_lshlrev_b32_e32 v68, 16, v154
	v_and_b32_e32 v69, 0xffff0000, v154
	v_lshlrev_b32_e32 v70, 16, v155
	v_and_b32_e32 v71, 0xffff0000, v155
	s_waitcnt lgkmcnt(0)
	v_pk_fma_f32 v[64:65], v[66:67], v[70:71], v[64:65] op_sel_hi:[0,1,1]
	v_pk_fma_f32 v[62:63], v[66:67], v[68:69], v[62:63] op_sel_hi:[0,1,1]
	v_mul_f32_e32 v67, v63, v63
	v_mul_f32_e32 v68, v65, v65
	v_fmac_f32_e32 v67, v62, v62
	v_fmac_f32_e32 v68, v64, v64
	v_lshlrev_b32_e32 v72, 16, v152
	v_and_b32_e32 v73, 0xffff0000, v152
	v_lshlrev_b32_e32 v74, 16, v153
	v_and_b32_e32 v75, 0xffff0000, v153
	v_add_f32_e32 v67, v67, v68
	v_cvt_pk_bf16_f32 v62, v62, v63
	v_cvt_pk_bf16_f32 v63, v64, v65
	v_lshl_add_u64 v[64:65], s[70:71], 0, v[144:145]
	v_lshl_add_u64 v[64:65], v[140:141], 1, v[64:65]
	v_pk_fma_f32 v[60:61], v[66:67], v[74:75], v[60:61] op_sel_hi:[0,1,1]
	v_pk_fma_f32 v[58:59], v[66:67], v[72:73], v[58:59] op_sel_hi:[0,1,1]
	v_lshlrev_b32_e32 v76, 16, v150
	v_and_b32_e32 v77, 0xffff0000, v150
	v_lshlrev_b32_e32 v78, 16, v151
	v_and_b32_e32 v79, 0xffff0000, v151
	global_store_dwordx2 v[64:65], v[62:63], off
	v_mul_f32_e32 v62, v59, v59
	v_mul_f32_e32 v63, v61, v61
	v_fmac_f32_e32 v62, v58, v58
	v_fmac_f32_e32 v63, v60, v60
	v_pk_fma_f32 v[56:57], v[66:67], v[78:79], v[56:57] op_sel_hi:[0,1,1]
	v_pk_fma_f32 v[54:55], v[66:67], v[76:77], v[54:55] op_sel_hi:[0,1,1]
	v_add_f32_e32 v62, v62, v63
	v_cvt_pk_bf16_f32 v58, v58, v59
	v_mul_f32_e32 v59, v55, v55
	v_mul_f32_e32 v63, v57, v57
	v_fmac_f32_e32 v59, v54, v54
	v_fmac_f32_e32 v63, v56, v56
	v_lshlrev_b32_e32 v80, 16, v148
	v_and_b32_e32 v81, 0xffff0000, v148
	v_lshlrev_b32_e32 v94, 16, v149
	v_and_b32_e32 v95, 0xffff0000, v149
	v_add_f32_e32 v62, v67, v62
	v_add_f32_e32 v59, v59, v63
	v_add_f32_e32 v59, v62, v59
	v_pk_fma_f32 v[52:53], v[66:67], v[94:95], v[52:53] op_sel_hi:[0,1,1]
	v_pk_fma_f32 v[62:63], v[66:67], v[80:81], v[50:51] op_sel_hi:[0,1,1]
	v_mul_f32_e32 v50, v63, v63
	v_mul_f32_e32 v51, v53, v53
	v_fmac_f32_e32 v50, v62, v62
	v_fmac_f32_e32 v51, v52, v52
	v_add_f32_e32 v50, v50, v51
	v_add_f32_e32 v50, v59, v50
	v_mov_b32_e32 v51, v50
	s_nop 1
	v_permlane16_swap_b32_e32 v51, v50
	v_cvt_pk_bf16_f32 v59, v60, v61
	global_store_dwordx2 v[64:65], v[58:59], off offset:32
	v_cvt_pk_bf16_f32 v54, v54, v55
	v_cvt_pk_bf16_f32 v55, v56, v57
	s_waitcnt lgkmcnt(0)
	v_add_f32_e32 v50, v50, v51
	v_mov_b32_e32 v51, v50
	s_nop 1
	v_permlane32_swap_b32_e32 v51, v50
	global_store_dwordx2 v[64:65], v[54:55], off offset:256
	v_cvt_pk_bf16_f32 v54, v62, v63
	v_cvt_pk_bf16_f32 v55, v52, v53
	global_store_dwordx2 v[64:65], v[54:55], off offset:288
	s_and_saveexec_b64 s[22:23], s[4:5]
	s_cbranch_execz .LBB0_664
	v_lshl_add_u64 v[52:53], v[142:143], 2, s[6:7]
	s_waitcnt lgkmcnt(0)
	v_add_f32_e32 v50, v50, v51
	global_atomic_add_f32 v[52:53], v50, off
; __device__ __forceinline__ unsigned cvt_pk_bf16(float lo, float hi) { unsigned r; asm volatile("v_cvt_pk_bf16_f32 %0, %1, %2" : "=v"(r) : "v"(lo), "v"(hi)); return r; }
;     __device__ __forceinline__ void operator()(const f32x4 (&acc)[2][2][4][2], const Unit& u, int wr, int wc, int fr, int fq) const {
;     ...
; #pragma unroll
;             for (int bj = 0; bj < 2; ++bj)
; #pragma unroll
;                 for (int n = 0; n < 2; ++n) {
;                     const f32x4 o = HAS_NRM ? (bs[bj][n] * r2[g] + acc[ai][bj][m][n]) : (bs[bj][n] + acc[ai][bj][m][n] * r2[g]);
;                     if (HAS_OUT) *(f32x4*)(out + off + bj * HALF + n * 16) = o;
;                     s += (o[0] * o[0] + o[1] * o[1]) + (o[2] * o[2] + o[3] * o[3]);
;                     if (HAS_OUTB) { u32x2 w; w.x = cvt_pk_bf16(o[0], o[1]); w.y = cvt_pk_bf16(o[2], o[3]); *(u32x2*)(outb + off + bj * HALF + n * 16) = w; }
;                 }
;             s += __shfl_xor(s, 16); s += __shfl_xor(s, 32);
;             if (fq == 0) unsafeAtomicAdd(ssq + row, s);
.LBB0_664:
	s_or_b64 exec, exec, s[22:23]
	v_fmamk_f32 v50, v204, 0x3a000000, v200
	v_sqrt_f32_e32 v50, v50
	s_waitcnt vmcnt(27)
	v_lshlrev_b32_e32 v52, 16, v124
	v_and_b32_e32 v53, 0xffff0000, v124
	v_lshlrev_b32_e32 v54, 16, v125
	v_and_b32_e32 v55, 0xffff0000, v125
	s_waitcnt lgkmcnt(0)
	v_pk_fma_f32 v[48:49], v[50:51], v[54:55], v[48:49] op_sel_hi:[0,1,1]
	v_pk_fma_f32 v[46:47], v[50:51], v[52:53], v[46:47] op_sel_hi:[0,1,1]
	v_mul_f32_e32 v51, v47, v47
	v_mul_f32_e32 v52, v49, v49
	v_fmac_f32_e32 v51, v46, v46
	v_fmac_f32_e32 v52, v48, v48
	s_waitcnt vmcnt(26)
	v_lshlrev_b32_e32 v56, 16, v122
	v_and_b32_e32 v57, 0xffff0000, v122
	v_lshlrev_b32_e32 v58, 16, v123
	v_and_b32_e32 v59, 0xffff0000, v123
	v_add_f32_e32 v51, v51, v52
	v_cvt_pk_bf16_f32 v46, v46, v47
	v_cvt_pk_bf16_f32 v47, v48, v49
	v_lshl_add_u64 v[48:49], s[70:71], 0, v[116:117]
	v_lshl_add_u64 v[48:49], v[140:141], 1, v[48:49]
	v_pk_fma_f32 v[44:45], v[50:51], v[58:59], v[44:45] op_sel_hi:[0,1,1]
	v_pk_fma_f32 v[42:43], v[50:51], v[56:57], v[42:43] op_sel_hi:[0,1,1]
	s_waitcnt vmcnt(25)
	v_lshlrev_b32_e32 v60, 16, v120
	v_and_b32_e32 v61, 0xffff0000, v120
	v_lshlrev_b32_e32 v62, 16, v121
	v_and_b32_e32 v63, 0xffff0000, v121
	global_store_dwordx2 v[48:49], v[46:47], off
	v_mul_f32_e32 v46, v43, v43
	v_mul_f32_e32 v47, v45, v45
	v_fmac_f32_e32 v46, v42, v42
	v_fmac_f32_e32 v47, v44, v44
	v_pk_fma_f32 v[40:41], v[50:51], v[62:63], v[40:41] op_sel_hi:[0,1,1]
	v_pk_fma_f32 v[38:39], v[50:51], v[60:61], v[38:39] op_sel_hi:[0,1,1]
	v_add_f32_e32 v46, v46, v47
	v_cvt_pk_bf16_f32 v42, v42, v43
	v_mul_f32_e32 v43, v39, v39
	v_mul_f32_e32 v47, v41, v41
	v_fmac_f32_e32 v43, v38, v38
	v_fmac_f32_e32 v47, v40, v40
	s_waitcnt vmcnt(25)
	v_lshlrev_b32_e32 v64, 16, v118
	v_and_b32_e32 v65, 0xffff0000, v118
	v_lshlrev_b32_e32 v66, 16, v119
	v_and_b32_e32 v67, 0xffff0000, v119
	v_add_f32_e32 v46, v51, v46
	v_add_f32_e32 v43, v43, v47
	v_add_f32_e32 v43, v46, v43
	v_pk_fma_f32 v[36:37], v[50:51], v[66:67], v[36:37] op_sel_hi:[0,1,1]
	v_pk_fma_f32 v[46:47], v[50:51], v[64:65], v[34:35] op_sel_hi:[0,1,1]
	v_mul_f32_e32 v34, v47, v47
	v_mul_f32_e32 v35, v37, v37
	v_fmac_f32_e32 v34, v46, v46
	v_fmac_f32_e32 v35, v36, v36
	v_add_f32_e32 v34, v34, v35
	v_add_f32_e32 v34, v43, v34
	v_mov_b32_e32 v35, v34
	s_nop 1
	v_permlane16_swap_b32_e32 v35, v34
	v_cvt_pk_bf16_f32 v43, v44, v45
	global_store_dwordx2 v[48:49], v[42:43], off offset:32
	v_cvt_pk_bf16_f32 v38, v38, v39
	v_cvt_pk_bf16_f32 v39, v40, v41
	s_waitcnt lgkmcnt(0)
	v_add_f32_e32 v34, v34, v35
	v_mov_b32_e32 v35, v34
	s_nop 1
	v_permlane32_swap_b32_e32 v35, v34
	global_store_dwordx2 v[48:49], v[38:39], off offset:256
	v_cvt_pk_bf16_f32 v38, v46, v47
	v_cvt_pk_bf16_f32 v39, v36, v37
	global_store_dwordx2 v[48:49], v[38:39], off offset:288
	s_and_saveexec_b64 s[22:23], s[4:5]
	s_cbranch_execz .LBB0_666
	v_lshl_add_u64 v[36:37], v[114:115], 2, s[6:7]
	s_waitcnt lgkmcnt(0)
	v_add_f32_e32 v34, v34, v35
	global_atomic_add_f32 v[36:37], v34, off
; __device__ __forceinline__ unsigned cvt_pk_bf16(float lo, float hi) { unsigned r; asm volatile("v_cvt_pk_bf16_f32 %0, %1, %2" : "=v"(r) : "v"(lo), "v"(hi)); return r; }
;     __device__ __forceinline__ void operator()(const f32x4 (&acc)[2][2][4][2], const Unit& u, int wr, int wc, int fr, int fq) const {
;     ...
; #pragma unroll
;             for (int bj = 0; bj < 2; ++bj)
; #pragma unroll
;                 for (int n = 0; n < 2; ++n) {
;                     const f32x4 o = HAS_NRM ? (bs[bj][n] * r2[g] + acc[ai][bj][m][n]) : (bs[bj][n] + acc[ai][bj][m][n] * r2[g]);
;                     if (HAS_OUT) *(f32x4*)(out + off + bj * HALF + n * 16) = o;
;                     s += (o[0] * o[0] + o[1] * o[1]) + (o[2] * o[2] + o[3] * o[3]);
;                     if (HAS_OUTB) { u32x2 w; w.x = cvt_pk_bf16(o[0], o[1]); w.y = cvt_pk_bf16(o[2], o[3]); *(u32x2*)(outb + off + bj * HALF + n * 16) = w; }
;                 }
;             s += __shfl_xor(s, 16); s += __shfl_xor(s, 32);
;             if (fq == 0) unsafeAtomicAdd(ssq + row, s);
.LBB0_666:
	s_or_b64 exec, exec, s[22:23]
	v_fmamk_f32 v34, v203, 0x3a000000, v200
	v_sqrt_f32_e32 v34, v34
	s_waitcnt vmcnt(23)
	v_lshlrev_b32_e32 v36, 16, v108
	v_and_b32_e32 v37, 0xffff0000, v108
	v_lshlrev_b32_e32 v38, 16, v109
	v_and_b32_e32 v39, 0xffff0000, v109
	s_waitcnt lgkmcnt(0)
	v_pk_fma_f32 v[32:33], v[34:35], v[38:39], v[32:33] op_sel_hi:[0,1,1]
	v_pk_fma_f32 v[30:31], v[34:35], v[36:37], v[30:31] op_sel_hi:[0,1,1]
	v_mul_f32_e32 v35, v31, v31
	v_mul_f32_e32 v36, v33, v33
	v_fmac_f32_e32 v35, v30, v30
	v_fmac_f32_e32 v36, v32, v32
	s_waitcnt vmcnt(22)
	v_lshlrev_b32_e32 v40, 16, v106
	v_and_b32_e32 v41, 0xffff0000, v106
	v_lshlrev_b32_e32 v42, 16, v107
	v_and_b32_e32 v43, 0xffff0000, v107
	v_add_f32_e32 v35, v35, v36
	v_cvt_pk_bf16_f32 v30, v30, v31
	v_cvt_pk_bf16_f32 v31, v32, v33
	v_lshl_add_u64 v[32:33], s[70:71], 0, v[100:101]
	v_lshl_add_u64 v[32:33], v[140:141], 1, v[32:33]
	v_pk_fma_f32 v[28:29], v[34:35], v[42:43], v[28:29] op_sel_hi:[0,1,1]
	v_pk_fma_f32 v[26:27], v[34:35], v[40:41], v[26:27] op_sel_hi:[0,1,1]
	s_waitcnt vmcnt(21)
	v_lshlrev_b32_e32 v44, 16, v104
	v_and_b32_e32 v45, 0xffff0000, v104
	v_lshlrev_b32_e32 v46, 16, v105
	v_and_b32_e32 v47, 0xffff0000, v105
	global_store_dwordx2 v[32:33], v[30:31], off
	v_mul_f32_e32 v30, v27, v27
	v_mul_f32_e32 v31, v29, v29
	v_fmac_f32_e32 v30, v26, v26
	v_fmac_f32_e32 v31, v28, v28
	v_pk_fma_f32 v[24:25], v[34:35], v[46:47], v[24:25] op_sel_hi:[0,1,1]
	v_pk_fma_f32 v[22:23], v[34:35], v[44:45], v[22:23] op_sel_hi:[0,1,1]
	v_add_f32_e32 v30, v30, v31
	v_cvt_pk_bf16_f32 v26, v26, v27
	v_mul_f32_e32 v27, v23, v23
	v_mul_f32_e32 v31, v25, v25
	v_fmac_f32_e32 v27, v22, v22
	v_fmac_f32_e32 v31, v24, v24
	s_waitcnt vmcnt(21)
	v_lshlrev_b32_e32 v48, 16, v102
	v_and_b32_e32 v49, 0xffff0000, v102
	v_lshlrev_b32_e32 v50, 16, v103
	v_and_b32_e32 v51, 0xffff0000, v103
	v_add_f32_e32 v30, v35, v30
	v_add_f32_e32 v27, v27, v31
	v_add_f32_e32 v27, v30, v27
	v_pk_fma_f32 v[20:21], v[34:35], v[50:51], v[20:21] op_sel_hi:[0,1,1]
	v_pk_fma_f32 v[30:31], v[34:35], v[48:49], v[18:19] op_sel_hi:[0,1,1]
	v_mul_f32_e32 v18, v31, v31
	v_mul_f32_e32 v19, v21, v21
	v_fmac_f32_e32 v18, v30, v30
	v_fmac_f32_e32 v19, v20, v20
	v_add_f32_e32 v18, v18, v19
	v_add_f32_e32 v18, v27, v18
	v_mov_b32_e32 v19, v18
	s_nop 1
	v_permlane16_swap_b32_e32 v19, v18
	v_cvt_pk_bf16_f32 v27, v28, v29
	global_store_dwordx2 v[32:33], v[26:27], off offset:32
	v_cvt_pk_bf16_f32 v22, v22, v23
	v_cvt_pk_bf16_f32 v23, v24, v25
	s_waitcnt lgkmcnt(0)
	v_add_f32_e32 v18, v18, v19
	v_mov_b32_e32 v19, v18
	s_nop 1
	v_permlane32_swap_b32_e32 v19, v18
	global_store_dwordx2 v[32:33], v[22:23], off offset:256
	v_cvt_pk_bf16_f32 v22, v30, v31
	v_cvt_pk_bf16_f32 v23, v20, v21
	global_store_dwordx2 v[32:33], v[22:23], off offset:288
	s_and_saveexec_b64 s[22:23], s[4:5]
	s_cbranch_execz .LBB0_668
	v_lshl_add_u64 v[20:21], v[98:99], 2, s[6:7]
	s_waitcnt lgkmcnt(0)
	v_add_f32_e32 v18, v18, v19
	global_atomic_add_f32 v[20:21], v18, off
.LBB0_668:
	s_or_b64 exec, exec, s[22:23]
	v_fmamk_f32 v18, v202, 0x3a000000, v200
	v_sqrt_f32_e32 v18, v18
	s_waitcnt vmcnt(19)
	v_lshlrev_b32_e32 v20, 16, v92
	v_and_b32_e32 v21, 0xffff0000, v92
	v_lshlrev_b32_e32 v22, 16, v93
	v_and_b32_e32 v23, 0xffff0000, v93
	s_waitcnt lgkmcnt(0)
	v_pk_fma_f32 v[16:17], v[18:19], v[22:23], v[16:17] op_sel_hi:[0,1,1]
	v_pk_fma_f32 v[14:15], v[18:19], v[20:21], v[14:15] op_sel_hi:[0,1,1]
	v_mul_f32_e32 v19, v15, v15
	v_mul_f32_e32 v20, v17, v17
	v_fmac_f32_e32 v19, v14, v14
	v_fmac_f32_e32 v20, v16, v16
	s_waitcnt vmcnt(18)
	v_lshlrev_b32_e32 v24, 16, v90
	v_and_b32_e32 v25, 0xffff0000, v90
	v_lshlrev_b32_e32 v26, 16, v91
	v_and_b32_e32 v27, 0xffff0000, v91
	v_add_f32_e32 v19, v19, v20
	v_cvt_pk_bf16_f32 v14, v14, v15
	v_cvt_pk_bf16_f32 v15, v16, v17
	v_lshl_add_u64 v[16:17], s[70:71], 0, v[84:85]
	v_lshl_add_u64 v[16:17], v[140:141], 1, v[16:17]
	v_pk_fma_f32 v[12:13], v[18:19], v[26:27], v[12:13] op_sel_hi:[0,1,1]
	v_pk_fma_f32 v[10:11], v[18:19], v[24:25], v[10:11] op_sel_hi:[0,1,1]
	s_waitcnt vmcnt(17)
	v_lshlrev_b32_e32 v28, 16, v88
	v_and_b32_e32 v29, 0xffff0000, v88
	v_lshlrev_b32_e32 v30, 16, v89
	v_and_b32_e32 v31, 0xffff0000, v89
	global_store_dwordx2 v[16:17], v[14:15], off
	v_mul_f32_e32 v14, v11, v11
	v_mul_f32_e32 v15, v13, v13
	v_fmac_f32_e32 v14, v10, v10
	v_fmac_f32_e32 v15, v12, v12
	v_pk_fma_f32 v[8:9], v[18:19], v[30:31], v[8:9] op_sel_hi:[0,1,1]
	v_pk_fma_f32 v[6:7], v[18:19], v[28:29], v[6:7] op_sel_hi:[0,1,1]
	v_add_f32_e32 v14, v14, v15
	v_cvt_pk_bf16_f32 v10, v10, v11
	v_mul_f32_e32 v11, v7, v7
	v_mul_f32_e32 v15, v9, v9
	v_fmac_f32_e32 v11, v6, v6
	v_fmac_f32_e32 v15, v8, v8
	s_waitcnt vmcnt(17)
	v_lshlrev_b32_e32 v32, 16, v86
	v_and_b32_e32 v33, 0xffff0000, v86
	v_lshlrev_b32_e32 v34, 16, v87
	v_and_b32_e32 v35, 0xffff0000, v87
	v_add_f32_e32 v14, v19, v14
	v_add_f32_e32 v11, v11, v15
	v_add_f32_e32 v11, v14, v11
	v_pk_fma_f32 v[4:5], v[18:19], v[34:35], v[4:5] op_sel_hi:[0,1,1]
	v_pk_fma_f32 v[14:15], v[18:19], v[32:33], v[2:3] op_sel_hi:[0,1,1]
	v_mul_f32_e32 v2, v15, v15
	v_mul_f32_e32 v3, v5, v5
	v_fmac_f32_e32 v2, v14, v14
	v_fmac_f32_e32 v3, v4, v4
	v_add_f32_e32 v2, v2, v3
	v_add_f32_e32 v2, v11, v2
	v_mov_b32_e32 v3, v2
	s_nop 1
	v_permlane16_swap_b32_e32 v3, v2
	v_cvt_pk_bf16_f32 v11, v12, v13
	global_store_dwordx2 v[16:17], v[10:11], off offset:32
	v_cvt_pk_bf16_f32 v6, v6, v7
	v_cvt_pk_bf16_f32 v7, v8, v9
	s_waitcnt lgkmcnt(0)
	v_add_f32_e32 v2, v2, v3
	v_mov_b32_e32 v3, v2
	s_nop 1
	v_permlane32_swap_b32_e32 v3, v2
	global_store_dwordx2 v[16:17], v[6:7], off offset:256
	v_cvt_pk_bf16_f32 v6, v14, v15
	v_cvt_pk_bf16_f32 v7, v4, v5
	global_store_dwordx2 v[16:17], v[6:7], off offset:288
	s_and_saveexec_b64 s[22:23], s[4:5]
	s_cbranch_execz .LBB0_670
	v_lshl_add_u64 v[4:5], v[82:83], 2, s[6:7]
	s_waitcnt lgkmcnt(0)
	v_add_f32_e32 v2, v2, v3
	global_atomic_add_f32 v[4:5], v2, off
